# v051 g3 converters 20 items per wave, barrier sequence 57856 items
# speedup vs baseline: 1.0029x; 1.0029x over previous
; #define WAIT_VM(n) do {} while (0)
; #define LAUNDER_S(x) do {} while (0)
; #define WAIT_VM(n) asm volatile("s_waitcnt vmcnt(" #n ")" ::: "memory")
; #define LAUNDER_S(x) asm volatile("" : "+s"(x))
; DEV int lane_id() { return (int)__builtin_amdgcn_mbcnt_hi(~0u, __builtin_amdgcn_mbcnt_lo(~0u, 0u)); }
; DEV void xcd_barrier(const XcdBarrier& b) {
;     WAIT_VM(0);
;     __syncthreads();
;     int bw = b.wave; LAUNDER_S(bw);
;     if (bw == 0 && lane_id() == 0) {
; DEV void phase_prologue_a(const Frame& F0) {
;     ...
;         constexpr int GU_NB = 2 * FF / 32, GU_ITEMS = 16 * GU_NB;
;         for (int it = F.gw; it < NE * GU_ITEMS; it += F.NGW) { const int e = it / GU_ITEMS, r = it % GU_ITEMS, kb = r / GU_NB, nb = r % GU_NB; const int d0 = 32 * nb, j = d0 >> 8, w = d0 & 255;
.LBB0_115:
	s_or_b64 exec, exec, s[30:31]
	s_cselect_b32 s38, 1, 0
	v_writelane_b32 v255, s38, 61
	v_readlane_b32 s38, v255, 59
	s_add_i32 s39, s38, 1
	v_writelane_b32 v255, s39, 59
	s_mov_b32 s41, 0
	v_readlane_b32 s39, v251, 29
	s_cmp_eq_u32 s39, 0
	s_cbranch_scc1 .Lbw0_none
	v_readlane_b32 s40, v255, 51
	s_cmp_lg_u32 s40, 0x100
	s_cbranch_scc1 .Lbw0_none
	v_readlane_b32 s40, v255, 48
	s_mul_i32 s40, s40, 7
	s_mul_i32 s38, s38, 0x700
	s_add_i32 s40, s40, s38
	s_add_i32 s40, s40, s39
	s_add_i32 s40, s40, -1
	s_cmp_lt_u32 s40, 0xe200
	s_cbranch_scc0 .Lbw0_none
	s_mov_b32 s41, 0
	s_add_i32 s40, s40, 0x4b00
	s_cmp_lt_u32 s40, 0x8000
	s_cbranch_scc1 .Lbw0_have
	s_mov_b32 s41, 1
	s_sub_i32 s40, s40, 0x8000
	s_cmp_lt_u32 s40, 0x3500
	s_cbranch_scc1 .Lbw0_have
	s_mov_b32 s41, 2
	s_sub_i32 s40, s40, 0x3500
	s_cmp_lt_u32 s40, 0x2b00
	s_cbranch_scc1 .Lbw0_have
	s_mov_b32 s41, 3
	s_sub_i32 s40, s40, 0x2b00

; #define WAIT_VM(n) do {} while (0)
; #define LAUNDER_S(x) do {} while (0)
; #define WAIT_VM(n) asm volatile("s_waitcnt vmcnt(" #n ")" ::: "memory")
; #define LAUNDER_S(x) asm volatile("" : "+s"(x))
; DEV int lane_id() { return (int)__builtin_amdgcn_mbcnt_hi(~0u, __builtin_amdgcn_mbcnt_lo(~0u, 0u)); }
; DEV void xcd_barrier(const XcdBarrier& b) {
;     WAIT_VM(0);
;     __syncthreads();
;     int bw = b.wave; LAUNDER_S(bw);
;     if (bw == 0 && lane_id() == 0) {
; DEV void phase_prologue_a(const Frame& F0) {
;     ...
;         constexpr int GU_NB = 2 * FF / 32, GU_ITEMS = 16 * GU_NB;
;         for (int it = F.gw; it < NE * GU_ITEMS; it += F.NGW) { const int e = it / GU_ITEMS, r = it % GU_ITEMS, kb = r / GU_NB, nb = r % GU_NB; const int d0 = 32 * nb, j = d0 >> 8, w = d0 & 255;
.LBB0_241:
	v_writelane_b32 v253, s58, 51
	s_nop 1
	v_writelane_b32 v253, s59, 52
	v_writelane_b32 v253, s56, 53
	s_nop 1
	v_writelane_b32 v253, s57, 54
	s_or_b64 exec, exec, s[34:35]
	s_cselect_b32 s38, 1, 0
	v_writelane_b32 v255, s38, 61
	v_readlane_b32 s38, v255, 59
	s_add_i32 s39, s38, 1
	v_writelane_b32 v255, s39, 59
	s_mov_b32 s41, 0
	v_readlane_b32 s39, v251, 29
	s_cmp_eq_u32 s39, 0
	s_cbranch_scc1 .Lbw2_none
	v_readlane_b32 s40, v255, 51
	s_cmp_lg_u32 s40, 0x100
	s_cbranch_scc1 .Lbw2_none
	v_readlane_b32 s40, v255, 48
	s_mul_i32 s40, s40, 7
	s_mul_i32 s38, s38, 0x700
	s_add_i32 s40, s40, s38
	s_add_i32 s40, s40, s39
	s_add_i32 s40, s40, -1
	s_cmp_lt_u32 s40, 0xe200
	s_cbranch_scc0 .Lbw2_none
	s_mov_b32 s41, 0
	s_add_i32 s40, s40, 0x4b00
	s_cmp_lt_u32 s40, 0x8000
	s_cbranch_scc1 .Lbw2_have
	s_mov_b32 s41, 1
	s_sub_i32 s40, s40, 0x8000
	s_cmp_lt_u32 s40, 0x3500
	s_cbranch_scc1 .Lbw2_have
	s_mov_b32 s41, 2
	s_sub_i32 s40, s40, 0x3500
	s_cmp_lt_u32 s40, 0x2b00
	s_cbranch_scc1 .Lbw2_have
	s_mov_b32 s41, 3
	s_sub_i32 s40, s40, 0x2b00

; #define WAIT_VM(n) do {} while (0)
; #define LAUNDER_S(x) do {} while (0)
; #define WAIT_VM(n) asm volatile("s_waitcnt vmcnt(" #n ")" ::: "memory")
; #define LAUNDER_S(x) asm volatile("" : "+s"(x))
; DEV int lane_id() { return (int)__builtin_amdgcn_mbcnt_hi(~0u, __builtin_amdgcn_mbcnt_lo(~0u, 0u)); }
; DEV void xcd_barrier(const XcdBarrier& b) {
;     WAIT_VM(0);
;     __syncthreads();
;     int bw = b.wave; LAUNDER_S(bw);
;     if (bw == 0 && lane_id() == 0) {
; DEV void phase_prologue_a(const Frame& F0) {
;     ...
;         constexpr int GU_NB = 2 * FF / 32, GU_ITEMS = 16 * GU_NB;
;         for (int it = F.gw; it < NE * GU_ITEMS; it += F.NGW) { const int e = it / GU_ITEMS, r = it % GU_ITEMS, kb = r / GU_NB, nb = r % GU_NB; const int d0 = 32 * nb, j = d0 >> 8, w = d0 & 255;
.LBB0_422:
	s_or_b64 exec, exec, s[34:35]
	s_cselect_b32 s38, 1, 0
	v_writelane_b32 v255, s38, 61
	v_readlane_b32 s38, v255, 59
	s_add_i32 s39, s38, 1
	v_writelane_b32 v255, s39, 59
	s_mov_b32 s41, 0
	v_readlane_b32 s39, v251, 29
	s_cmp_eq_u32 s39, 0
	s_cbranch_scc1 .Lbw3_none
	v_readlane_b32 s40, v255, 51
	s_cmp_lg_u32 s40, 0x100
	s_cbranch_scc1 .Lbw3_none
	v_readlane_b32 s40, v255, 48
	s_mul_i32 s40, s40, 7
	s_mul_i32 s38, s38, 0x700
	s_add_i32 s40, s40, s38
	s_add_i32 s40, s40, s39
	s_add_i32 s40, s40, -1
	s_cmp_lt_u32 s40, 0xe200
	s_cbranch_scc0 .Lbw3_none
	s_mov_b32 s41, 0
	s_add_i32 s40, s40, 0x4b00
	s_cmp_lt_u32 s40, 0x8000
	s_cbranch_scc1 .Lbw3_have
	s_mov_b32 s41, 1
	s_sub_i32 s40, s40, 0x8000
	s_cmp_lt_u32 s40, 0x3500
	s_cbranch_scc1 .Lbw3_have
	s_mov_b32 s41, 2
	s_sub_i32 s40, s40, 0x3500
	s_cmp_lt_u32 s40, 0x2b00
	s_cbranch_scc1 .Lbw3_have
	s_mov_b32 s41, 3
	s_sub_i32 s40, s40, 0x2b00

; #define WAIT_VM(n) do {} while (0)
; #define LAUNDER_S(x) do {} while (0)
; #define WAIT_VM(n) asm volatile("s_waitcnt vmcnt(" #n ")" ::: "memory")
; #define LAUNDER_S(x) asm volatile("" : "+s"(x))
; DEV int lane_id() { return (int)__builtin_amdgcn_mbcnt_hi(~0u, __builtin_amdgcn_mbcnt_lo(~0u, 0u)); }
; DEV void xcd_barrier(const XcdBarrier& b) {
;     WAIT_VM(0);
;     __syncthreads();
;     int bw = b.wave; LAUNDER_S(bw);
;     if (bw == 0 && lane_id() == 0) {
; DEV void phase_prologue_a(const Frame& F0) {
;     ...
;         constexpr int GU_NB = 2 * FF / 32, GU_ITEMS = 16 * GU_NB;
;         for (int it = F.gw; it < NE * GU_ITEMS; it += F.NGW) { const int e = it / GU_ITEMS, r = it % GU_ITEMS, kb = r / GU_NB, nb = r % GU_NB; const int d0 = 32 * nb, j = d0 >> 8, w = d0 & 255;
.Lxb4_join:
.LBB0_811:
	s_or_b64 exec, exec, s[34:35]
	s_cselect_b32 s38, 1, 0
	v_writelane_b32 v255, s38, 61
	v_readlane_b32 s38, v255, 59
	s_add_i32 s39, s38, 1
	v_writelane_b32 v255, s39, 59
	s_mov_b32 s41, 0
	v_readlane_b32 s39, v251, 29
	s_cmp_eq_u32 s39, 0
	s_cbranch_scc1 .Lbw4_none
	v_readlane_b32 s40, v255, 51
	s_cmp_lg_u32 s40, 0x100
	s_cbranch_scc1 .Lbw4_none
	v_readlane_b32 s40, v255, 48
	s_mul_i32 s40, s40, 7
	s_mul_i32 s38, s38, 0x700
	s_add_i32 s40, s40, s38
	s_add_i32 s40, s40, s39
	s_add_i32 s40, s40, -1
	s_cmp_lt_u32 s40, 0xe200
	s_cbranch_scc0 .Lbw4_none
	s_mov_b32 s41, 0
	s_add_i32 s40, s40, 0x4b00
	s_cmp_lt_u32 s40, 0x8000
	s_cbranch_scc1 .Lbw4_have
	s_mov_b32 s41, 1
	s_sub_i32 s40, s40, 0x8000
	s_cmp_lt_u32 s40, 0x3500
	s_cbranch_scc1 .Lbw4_have
	s_mov_b32 s41, 2
	s_sub_i32 s40, s40, 0x3500
	s_cmp_lt_u32 s40, 0x2b00
	s_cbranch_scc1 .Lbw4_have
	s_mov_b32 s41, 3
	s_sub_i32 s40, s40, 0x2b00

; #define WAVE_LDS_SYNC() do { int _z = 0; (void)emu::wave_xchg(&_z, 4); } while (0)
; #define LAS __attribute__((address_space(3)))
; #define WAVE_LDS_SYNC() asm volatile("s_waitcnt lgkmcnt(0)" ::: "memory")
; #define NT_LOAD(p) __builtin_nontemporal_load(p)
; DEV void tr_item(const float* W, int ldw, int col0, int k0, bf16_t* WT, int K, int row0, LAS float* scr, int lane) {
;     ...
;     for (int i = 0; i < 32; ++i) { const int kk = 2 * i + (lane >> 5); scr[kk * 33 + (lane & 31)] = NT_LOAD(&W[(size_t)(k0 + kk) * ldw + col0 + (lane & 31)]); }
;     WAVE_LDS_SYNC();
;     const int c = lane & 7;
; #pragma unroll
;     for (int j = 0; j < 4; ++j) { const int n = (lane >> 3) + 8 * j; const LAS float* s = scr + (8 * c) * 33 + n;
; DEV void phase_prologue_a(const Frame& F0) {
;     ...
;         constexpr int GU_NB = 2 * FF / 32, GU_ITEMS = 16 * GU_NB;
;         for (int it = F.gw; it < NE * GU_ITEMS; it += F.NGW) { const int e = it / GU_ITEMS, r = it % GU_ITEMS, kb = r / GU_NB, nb = r % GU_NB; const int d0 = 32 * nb, j = d0 >> 8, w = d0 & 255;
;             const float* src = (w < 128 ? GIN(I_WGATE) : GIN(I_WUP)) + ((size_t)l * NE + e) * 1024 * FF;
;             tr_item(src, FF, 128 * j + (w & 127), 64 * kb, (bf16_t*)(F.ws + WS_WGU) + ((size_t)l * NE + e) * 2 * FF * 1024, 1024, d0, scr, F.lane); }
.Lsg_entry:
	v_readlane_b32 s36, v253, 62
	s_cmp_gt_u32 s36, 2
	s_cbranch_scc1 .Lsg_done
	v_readlane_b32 s2, v255, 51
	s_cmp_lg_u32 s2, 0x100
	s_cbranch_scc1 .Lsg_done
	v_readlane_b32 s2, v255, 48
	s_cmp_lt_u32 s2, 0x88
	s_cbranch_scc1 .Lsg_done
	v_readlane_b32 s3, v251, 29
	s_sub_i32 s2, s2, 0x88
	s_lshl_b32 s2, s2, 3
	s_add_i32 s2, s2, s3
	v_readlane_b32 s6, v255, 53
	v_readlane_b32 s7, v255, 54
	v_readlane_b32 s4, v255, 55
	v_readlane_b32 s5, v255, 56
	v_readlane_b32 s34, v255, 57
	v_readlane_b32 s35, v255, 58
	s_add_u32 s6, s6, 0x2bc8000
	s_addc_u32 s7, s7, 0
	s_mov_b32 s8, 0
	s_mov_b32 s37, 0
	s_cmp_eq_u32 s36, 0
	s_cbranch_scc1 .Lsg_go
	s_mov_b32 s8, 0x8000000
	s_mov_b32 s37, 0x3500
	s_cmp_eq_u32 s36, 1
	s_cbranch_scc1 .Lsg_go
	s_mov_b32 s8, 0x10000000
	s_mov_b32 s37, 0x2b00
.Lsg_go:
	s_add_u32 s4, s4, s8
	s_addc_u32 s5, s5, 0
	s_add_u32 s34, s34, s8
	s_addc_u32 s35, s35, 0
	s_add_u32 s6, s6, s8
	s_addc_u32 s7, s7, 0
	s_add_i32 s2, s2, s37
	s_add_i32 s101, s37, 0x4b00
	s_lshl_b32 s30, s3, 14
	v_and_b32_e32 v120, 31, v200
	v_lshlrev_b32_e32 v2, 2, v120
	v_lshrrev_b32_e32 v3, 5, v200
	v_and_b32_e32 v4, 7, v200
	v_lshrrev_b32_e32 v6, 3, v200
	v_mul_u32_u24_e32 v7, 33, v3
	v_add_u32_e32 v7, v7, v120
	v_lshl_add_u32 v7, v7, 2, s30
	v_add_u32_e32 v8, 0x400, v7
	v_add_u32_e32 v9, 0x840, v7
	v_add_u32_e32 v10, 0xc40, v7
	v_add_u32_e32 v11, 0x1080, v7
	v_add_u32_e32 v12, 0x1480, v7
	v_add_u32_e32 v13, 0x18c0, v7
	v_add_u32_e32 v14, 0x1cc0, v7
	v_mul_u32_u24_e32 v120, 0x108, v4
	v_add_u32_e32 v120, v120, v6
	v_lshl_add_u32 v15, v120, 2, s30
	v_lshl_add_u32 v122, v3, 13, v2
	v_mov_b32_e32 v123, 0
	v_lshlrev_b32_e32 v124, 4, v4
	v_lshl_add_u32 v124, v6, 11, v124
	v_mov_b32_e32 v125, 0
	s_mov_b64 s[40:41], 0x20000
	s_mov_b64 s[42:43], 0x4000
	s_mov_b64 s[44:45], 0x4000
